# P4 epilogue: straight-line fast paths for all common unit kinds (Qb, K, V, PB, gates) by uniform dispatch on the column panel; sample and conv-tail panels keep the original code
# speedup vs baseline: 1.0051x; 1.0051x over previous
; #define EM_PK8(a, b) ((u32x4){cvt_pk_bf16((a)[0], (a)[1]), cvt_pk_bf16((a)[2], (a)[3]), cvt_pk_bf16((b)[0], (b)[1]), cvt_pk_bf16((b)[2], (b)[3])})
;     __device__ __forceinline__ void operator()(const f32x4 (&acc)[2][2][4][2], const Unit& u, int wr, int wc, int fr, int fq) const {
;         const int pn = u.pn; const bool samp = u.pm * BM >= mp;
;         const int col0 = pn * BM + wc * 32 + 8 * fq;
;     ...
; #pragma unroll
;         for (int ai = 0; ai < 2; ++ai)
; #pragma unroll
;             for (int m = 0; m < 4; ++m) { const int row = u.pm * BM + ai * HALF + wr * 64 + m * 16 + fr;
; #pragma unroll
;                 for (int bj = 0; bj < 2; ++bj) { const int col = col0 + bj * HALF; const f32x4 v0 = acc[ai][bj][m][0], v1 = acc[ai][bj][m][1];
;                     if (samp || pn == 14) { float* pp = P + (size_t)row * 3840 + col; *(f32x4*)pp = v0; *(f32x4*)(pp + 4) = v1; }
;                     else if (pn >= 6) *(u32x4*)(PB + (size_t)row * 2048 + (col - 1536)) = EM_PK8(v0, v1);
;                     if (pn < 2) { if (!samp) { const f32x4 q0 = v0 * c2, q1 = v1 * c2; *(u32x4*)(Qb + (size_t)row * 512 + col) = EM_PK8(q0, q1); } }
;                     else if (pn < 4) { const int c = col - 512; float* ko = (samp ? out + o_ks + (size_t)(row - mp) * 512 : out + o_kp + (size_t)row * 512) + c; *(f32x4*)ko = v0; *(f32x4*)(ko + 4) = v1;
;                         if (!samp) *(u32x4*)(Kb + (size_t)row * 512 + c) = EM_PK8(v0, v1); }
;                     else if (pn < 6) { const int c = col - 1024; float* vo = (samp ? out + o_vs + (size_t)(row - mp) * 512 : out + o_vp + (size_t)row * 512) + c; *(f32x4*)vo = v0; *(f32x4*)(vo + 4) = v1;
;                         if (!samp) *(u32x4*)(Vb + (size_t)row * 512 + c) = EM_PK8(v0, v1); }
;                     else if (pn < 12) { const int c = col - 1536;
.LBB0_337:
	s_cmp_eq_u32 s8, 14
	s_cbranch_scc1 .Lp4epi_D
	s_cmp_lt_i32 s6, 64
	s_cbranch_scc0 .Lp4epi_generic
	s_cmp_lt_u32 s8, 2
	s_cbranch_scc1 .Lp4epi_B
	s_cmp_lt_u32 s8, 4
	s_cbranch_scc1 .Lp4epi_K
	s_cmp_lt_u32 s8, 6
	s_cbranch_scc1 .Lp4epi_V
	s_cmp_gt_u32 s8, 11
	s_cbranch_scc1 .Lp4epi_A
	s_and_b32 s98, s6, 7
	s_cmp_eq_u32 s98, 7
	s_cbranch_scc1 .Lp4epi_generic

; #define EM_PK8(a, b) ((u32x4){cvt_pk_bf16((a)[0], (a)[1]), cvt_pk_bf16((a)[2], (a)[3]), cvt_pk_bf16((b)[0], (b)[1]), cvt_pk_bf16((b)[2], (b)[3])})
;     __device__ __forceinline__ void operator()(const f32x4 (&acc)[2][2][4][2], const Unit& u, int wr, int wc, int fr, int fq) const {
;     ...
;                     if (pn < 2) { if (!samp) { const f32x4 q0 = v0 * c2, q1 = v1 * c2; *(u32x4*)(Qb + (size_t)row * 512 + col) = EM_PK8(q0, q1); } }
.Lp4epi_B:
	v_readlane_b32 s98, v244, 20
	v_readlane_b32 s99, v244, 21
	v_lshl_add_u32 v254, s6, 8, v1
	v_lshl_or_b32 v255, s8, 8, v163
	v_lshlrev_b32_e32 v254, 10, v254
	v_lshl_add_u32 v254, v255, 1, v254
	v_pk_mul_f32 v[126:127], v[126:127], s[84:85] op_sel_hi:[1,0]
	v_pk_mul_f32 v[128:129], v[128:129], s[84:85] op_sel_hi:[1,0]
	v_pk_mul_f32 v[122:123], v[122:123], s[84:85] op_sel_hi:[1,0]
	v_pk_mul_f32 v[124:125], v[124:125], s[84:85] op_sel_hi:[1,0]
	v_cvt_pk_bf16_f32 v246, v126, v127
	v_cvt_pk_bf16_f32 v247, v128, v129
	v_cvt_pk_bf16_f32 v248, v122, v123
	v_cvt_pk_bf16_f32 v249, v124, v125
	global_store_dwordx4 v254, v[246:249], s[98:99]
	v_pk_mul_f32 v[118:119], v[118:119], s[84:85] op_sel_hi:[1,0]
	v_pk_mul_f32 v[120:121], v[120:121], s[84:85] op_sel_hi:[1,0]
	v_pk_mul_f32 v[114:115], v[114:115], s[84:85] op_sel_hi:[1,0]
	v_pk_mul_f32 v[116:117], v[116:117], s[84:85] op_sel_hi:[1,0]
	v_cvt_pk_bf16_f32 v250, v118, v119
	v_cvt_pk_bf16_f32 v251, v120, v121
	v_cvt_pk_bf16_f32 v252, v114, v115
	v_cvt_pk_bf16_f32 v253, v116, v117
	global_store_dwordx4 v254, v[250:253], s[98:99] offset:256
	v_add_u32_e32 v255, 0x4000, v254
	v_pk_mul_f32 v[110:111], v[110:111], s[84:85] op_sel_hi:[1,0]
	v_pk_mul_f32 v[112:113], v[112:113], s[84:85] op_sel_hi:[1,0]
	v_pk_mul_f32 v[106:107], v[106:107], s[84:85] op_sel_hi:[1,0]
	v_pk_mul_f32 v[108:109], v[108:109], s[84:85] op_sel_hi:[1,0]
	v_cvt_pk_bf16_f32 v246, v110, v111
	v_cvt_pk_bf16_f32 v247, v112, v113
	v_cvt_pk_bf16_f32 v248, v106, v107
	v_cvt_pk_bf16_f32 v249, v108, v109
	global_store_dwordx4 v255, v[246:249], s[98:99]
	v_pk_mul_f32 v[102:103], v[102:103], s[84:85] op_sel_hi:[1,0]
	v_pk_mul_f32 v[104:105], v[104:105], s[84:85] op_sel_hi:[1,0]
	v_pk_mul_f32 v[98:99], v[98:99], s[84:85] op_sel_hi:[1,0]
	v_pk_mul_f32 v[100:101], v[100:101], s[84:85] op_sel_hi:[1,0]
	v_cvt_pk_bf16_f32 v250, v102, v103
	v_cvt_pk_bf16_f32 v251, v104, v105
	v_cvt_pk_bf16_f32 v252, v98, v99
	v_cvt_pk_bf16_f32 v253, v100, v101
	global_store_dwordx4 v255, v[250:253], s[98:99] offset:256
	v_add_u32_e32 v255, 0x8000, v254
	v_pk_mul_f32 v[94:95], v[94:95], s[84:85] op_sel_hi:[1,0]
	v_pk_mul_f32 v[96:97], v[96:97], s[84:85] op_sel_hi:[1,0]
	v_pk_mul_f32 v[90:91], v[90:91], s[84:85] op_sel_hi:[1,0]
	v_pk_mul_f32 v[92:93], v[92:93], s[84:85] op_sel_hi:[1,0]
	v_cvt_pk_bf16_f32 v246, v94, v95
	v_cvt_pk_bf16_f32 v247, v96, v97
	v_cvt_pk_bf16_f32 v248, v90, v91
	v_cvt_pk_bf16_f32 v249, v92, v93
	global_store_dwordx4 v255, v[246:249], s[98:99]
	v_pk_mul_f32 v[86:87], v[86:87], s[84:85] op_sel_hi:[1,0]
	v_pk_mul_f32 v[88:89], v[88:89], s[84:85] op_sel_hi:[1,0]
	v_pk_mul_f32 v[82:83], v[82:83], s[84:85] op_sel_hi:[1,0]
	v_pk_mul_f32 v[84:85], v[84:85], s[84:85] op_sel_hi:[1,0]
	v_cvt_pk_bf16_f32 v250, v86, v87
	v_cvt_pk_bf16_f32 v251, v88, v89
	v_cvt_pk_bf16_f32 v252, v82, v83
	v_cvt_pk_bf16_f32 v253, v84, v85
	global_store_dwordx4 v255, v[250:253], s[98:99] offset:256
	v_add_u32_e32 v255, 0xc000, v254
	v_pk_mul_f32 v[78:79], v[78:79], s[84:85] op_sel_hi:[1,0]
	v_pk_mul_f32 v[80:81], v[80:81], s[84:85] op_sel_hi:[1,0]
	v_pk_mul_f32 v[74:75], v[74:75], s[84:85] op_sel_hi:[1,0]
	v_pk_mul_f32 v[76:77], v[76:77], s[84:85] op_sel_hi:[1,0]
	v_cvt_pk_bf16_f32 v246, v78, v79
	v_cvt_pk_bf16_f32 v247, v80, v81
	v_cvt_pk_bf16_f32 v248, v74, v75
	v_cvt_pk_bf16_f32 v249, v76, v77
	global_store_dwordx4 v255, v[246:249], s[98:99]
	v_pk_mul_f32 v[70:71], v[70:71], s[84:85] op_sel_hi:[1,0]
	v_pk_mul_f32 v[72:73], v[72:73], s[84:85] op_sel_hi:[1,0]
	v_pk_mul_f32 v[66:67], v[66:67], s[84:85] op_sel_hi:[1,0]
	v_pk_mul_f32 v[68:69], v[68:69], s[84:85] op_sel_hi:[1,0]
	v_cvt_pk_bf16_f32 v250, v70, v71
	v_cvt_pk_bf16_f32 v251, v72, v73
	v_cvt_pk_bf16_f32 v252, v66, v67
	v_cvt_pk_bf16_f32 v253, v68, v69
	global_store_dwordx4 v255, v[250:253], s[98:99] offset:256
	v_add_u32_e32 v255, 0x20000, v254
	v_pk_mul_f32 v[62:63], v[62:63], s[84:85] op_sel_hi:[1,0]
	v_pk_mul_f32 v[64:65], v[64:65], s[84:85] op_sel_hi:[1,0]
	v_pk_mul_f32 v[58:59], v[58:59], s[84:85] op_sel_hi:[1,0]
	v_pk_mul_f32 v[60:61], v[60:61], s[84:85] op_sel_hi:[1,0]
	v_cvt_pk_bf16_f32 v246, v62, v63
	v_cvt_pk_bf16_f32 v247, v64, v65
	v_cvt_pk_bf16_f32 v248, v58, v59
	v_cvt_pk_bf16_f32 v249, v60, v61
	global_store_dwordx4 v255, v[246:249], s[98:99]
	v_pk_mul_f32 v[54:55], v[54:55], s[84:85] op_sel_hi:[1,0]
	v_pk_mul_f32 v[56:57], v[56:57], s[84:85] op_sel_hi:[1,0]
	v_pk_mul_f32 v[50:51], v[50:51], s[84:85] op_sel_hi:[1,0]
	v_pk_mul_f32 v[52:53], v[52:53], s[84:85] op_sel_hi:[1,0]
	v_cvt_pk_bf16_f32 v250, v54, v55
	v_cvt_pk_bf16_f32 v251, v56, v57
	v_cvt_pk_bf16_f32 v252, v50, v51
	v_cvt_pk_bf16_f32 v253, v52, v53
	global_store_dwordx4 v255, v[250:253], s[98:99] offset:256
	v_add_u32_e32 v255, 0x24000, v254
	v_pk_mul_f32 v[46:47], v[46:47], s[84:85] op_sel_hi:[1,0]
	v_pk_mul_f32 v[48:49], v[48:49], s[84:85] op_sel_hi:[1,0]
	v_pk_mul_f32 v[42:43], v[42:43], s[84:85] op_sel_hi:[1,0]
	v_pk_mul_f32 v[44:45], v[44:45], s[84:85] op_sel_hi:[1,0]
	v_cvt_pk_bf16_f32 v246, v46, v47
	v_cvt_pk_bf16_f32 v247, v48, v49
	v_cvt_pk_bf16_f32 v248, v42, v43
	v_cvt_pk_bf16_f32 v249, v44, v45
	global_store_dwordx4 v255, v[246:249], s[98:99]
	v_pk_mul_f32 v[38:39], v[38:39], s[84:85] op_sel_hi:[1,0]
	v_pk_mul_f32 v[40:41], v[40:41], s[84:85] op_sel_hi:[1,0]
	v_pk_mul_f32 v[34:35], v[34:35], s[84:85] op_sel_hi:[1,0]
	v_pk_mul_f32 v[36:37], v[36:37], s[84:85] op_sel_hi:[1,0]
	v_cvt_pk_bf16_f32 v250, v38, v39
	v_cvt_pk_bf16_f32 v251, v40, v41
	v_cvt_pk_bf16_f32 v252, v34, v35
	v_cvt_pk_bf16_f32 v253, v36, v37
	global_store_dwordx4 v255, v[250:253], s[98:99] offset:256
	v_add_u32_e32 v255, 0x28000, v254
; #define EM_PK8(a, b) ((u32x4){cvt_pk_bf16((a)[0], (a)[1]), cvt_pk_bf16((a)[2], (a)[3]), cvt_pk_bf16((b)[0], (b)[1]), cvt_pk_bf16((b)[2], (b)[3])})
;     __device__ __forceinline__ void operator()(const f32x4 (&acc)[2][2][4][2], const Unit& u, int wr, int wc, int fr, int fq) const {
;     ...
;                     if (pn < 2) { if (!samp) { const f32x4 q0 = v0 * c2, q1 = v1 * c2; *(u32x4*)(Qb + (size_t)row * 512 + col) = EM_PK8(q0, q1); } }
;                     else if (pn < 4) { const int c = col - 512; float* ko = (samp ? out + o_ks + (size_t)(row - mp) * 512 : out + o_kp + (size_t)row * 512) + c; *(f32x4*)ko = v0; *(f32x4*)(ko + 4) = v1;
;                         if (!samp) *(u32x4*)(Kb + (size_t)row * 512 + c) = EM_PK8(v0, v1); }
	v_pk_mul_f32 v[30:31], v[30:31], s[84:85] op_sel_hi:[1,0]
	v_pk_mul_f32 v[32:33], v[32:33], s[84:85] op_sel_hi:[1,0]
	v_pk_mul_f32 v[26:27], v[26:27], s[84:85] op_sel_hi:[1,0]
	v_pk_mul_f32 v[28:29], v[28:29], s[84:85] op_sel_hi:[1,0]
	v_cvt_pk_bf16_f32 v246, v30, v31
	v_cvt_pk_bf16_f32 v247, v32, v33
	v_cvt_pk_bf16_f32 v248, v26, v27
	v_cvt_pk_bf16_f32 v249, v28, v29
	global_store_dwordx4 v255, v[246:249], s[98:99]
	v_pk_mul_f32 v[22:23], v[22:23], s[84:85] op_sel_hi:[1,0]
	v_pk_mul_f32 v[24:25], v[24:25], s[84:85] op_sel_hi:[1,0]
	v_pk_mul_f32 v[18:19], v[18:19], s[84:85] op_sel_hi:[1,0]
	v_pk_mul_f32 v[20:21], v[20:21], s[84:85] op_sel_hi:[1,0]
	v_cvt_pk_bf16_f32 v250, v22, v23
	v_cvt_pk_bf16_f32 v251, v24, v25
	v_cvt_pk_bf16_f32 v252, v18, v19
	v_cvt_pk_bf16_f32 v253, v20, v21
	global_store_dwordx4 v255, v[250:253], s[98:99] offset:256
	v_add_u32_e32 v255, 0x2c000, v254
	v_pk_mul_f32 v[14:15], v[14:15], s[84:85] op_sel_hi:[1,0]
	v_pk_mul_f32 v[16:17], v[16:17], s[84:85] op_sel_hi:[1,0]
	v_pk_mul_f32 v[10:11], v[10:11], s[84:85] op_sel_hi:[1,0]
	v_pk_mul_f32 v[12:13], v[12:13], s[84:85] op_sel_hi:[1,0]
	v_cvt_pk_bf16_f32 v246, v14, v15
	v_cvt_pk_bf16_f32 v247, v16, v17
	v_cvt_pk_bf16_f32 v248, v10, v11
	v_cvt_pk_bf16_f32 v249, v12, v13
	global_store_dwordx4 v255, v[246:249], s[98:99]
	v_pk_mul_f32 v[6:7], v[6:7], s[84:85] op_sel_hi:[1,0]
	v_pk_mul_f32 v[8:9], v[8:9], s[84:85] op_sel_hi:[1,0]
	v_pk_mul_f32 v[2:3], v[2:3], s[84:85] op_sel_hi:[1,0]
	v_pk_mul_f32 v[4:5], v[4:5], s[84:85] op_sel_hi:[1,0]
	v_cvt_pk_bf16_f32 v250, v6, v7
	v_cvt_pk_bf16_f32 v251, v8, v9
	v_cvt_pk_bf16_f32 v252, v2, v3
	v_cvt_pk_bf16_f32 v253, v4, v5
	global_store_dwordx4 v255, v[250:253], s[98:99] offset:256
	s_branch .LBB0_945
.Lp4epi_K:
	v_readlane_b32 s98, v244, 22
	v_readlane_b32 s99, v244, 23
	v_lshl_add_u32 v254, s6, 8, v1
	v_lshl_or_b32 v255, s8, 8, v163
	v_lshlrev_b32_e32 v252, 11, v254
	v_lshl_add_u32 v252, v255, 2, v252
	v_add_u32_e32 v252, 0xfffff800, v252
	v_lshlrev_b32_e32 v253, 10, v254
	v_lshl_add_u32 v253, v255, 1, v253
	v_add_u32_e32 v253, 0xfffffc00, v253
	v_mov_b32_e32 v254, v252
	v_mov_b32_e32 v255, v253
	global_store_dwordx4 v254, v[126:129], s[74:75]
	global_store_dwordx4 v254, v[122:125], s[74:75] offset:16
	v_cvt_pk_bf16_f32 v246, v126, v127
	v_cvt_pk_bf16_f32 v247, v128, v129
	v_cvt_pk_bf16_f32 v248, v122, v123
	v_cvt_pk_bf16_f32 v249, v124, v125
	global_store_dwordx4 v255, v[246:249], s[98:99]
	s_nop 1
	global_store_dwordx4 v254, v[118:121], s[74:75] offset:512
	global_store_dwordx4 v254, v[114:117], s[74:75] offset:528
	v_cvt_pk_bf16_f32 v246, v118, v119
	v_cvt_pk_bf16_f32 v247, v120, v121
	v_cvt_pk_bf16_f32 v248, v114, v115
	v_cvt_pk_bf16_f32 v249, v116, v117
	global_store_dwordx4 v255, v[246:249], s[98:99] offset:256
	s_nop 1
	v_add_u32_e32 v254, 0x8000, v252
	v_add_u32_e32 v255, 0x4000, v253
	global_store_dwordx4 v254, v[110:113], s[74:75]
	global_store_dwordx4 v254, v[106:109], s[74:75] offset:16
	v_cvt_pk_bf16_f32 v246, v110, v111
	v_cvt_pk_bf16_f32 v247, v112, v113
	v_cvt_pk_bf16_f32 v248, v106, v107
	v_cvt_pk_bf16_f32 v249, v108, v109
	global_store_dwordx4 v255, v[246:249], s[98:99]
	s_nop 1
	global_store_dwordx4 v254, v[102:105], s[74:75] offset:512
	global_store_dwordx4 v254, v[98:101], s[74:75] offset:528
	v_cvt_pk_bf16_f32 v246, v102, v103
	v_cvt_pk_bf16_f32 v247, v104, v105
	v_cvt_pk_bf16_f32 v248, v98, v99
	v_cvt_pk_bf16_f32 v249, v100, v101
	global_store_dwordx4 v255, v[246:249], s[98:99] offset:256
	s_nop 1
	v_add_u32_e32 v254, 0x10000, v252
	v_add_u32_e32 v255, 0x8000, v253
	global_store_dwordx4 v254, v[94:97], s[74:75]
	global_store_dwordx4 v254, v[90:93], s[74:75] offset:16
	v_cvt_pk_bf16_f32 v246, v94, v95
	v_cvt_pk_bf16_f32 v247, v96, v97
	v_cvt_pk_bf16_f32 v248, v90, v91
	v_cvt_pk_bf16_f32 v249, v92, v93
	global_store_dwordx4 v255, v[246:249], s[98:99]
	s_nop 1
	global_store_dwordx4 v254, v[86:89], s[74:75] offset:512
	global_store_dwordx4 v254, v[82:85], s[74:75] offset:528
	v_cvt_pk_bf16_f32 v246, v86, v87
	v_cvt_pk_bf16_f32 v247, v88, v89
	v_cvt_pk_bf16_f32 v248, v82, v83
	v_cvt_pk_bf16_f32 v249, v84, v85
	global_store_dwordx4 v255, v[246:249], s[98:99] offset:256
	s_nop 1
	v_add_u32_e32 v254, 0x18000, v252
	v_add_u32_e32 v255, 0xc000, v253
	global_store_dwordx4 v254, v[78:81], s[74:75]
	global_store_dwordx4 v254, v[74:77], s[74:75] offset:16
	v_cvt_pk_bf16_f32 v246, v78, v79
	v_cvt_pk_bf16_f32 v247, v80, v81
	v_cvt_pk_bf16_f32 v248, v74, v75
	v_cvt_pk_bf16_f32 v249, v76, v77
	global_store_dwordx4 v255, v[246:249], s[98:99]
	s_nop 1
	global_store_dwordx4 v254, v[70:73], s[74:75] offset:512
	global_store_dwordx4 v254, v[66:69], s[74:75] offset:528
	v_cvt_pk_bf16_f32 v246, v70, v71
	v_cvt_pk_bf16_f32 v247, v72, v73
	v_cvt_pk_bf16_f32 v248, v66, v67
	v_cvt_pk_bf16_f32 v249, v68, v69
	global_store_dwordx4 v255, v[246:249], s[98:99] offset:256
	s_nop 1
	v_add_u32_e32 v254, 0x40000, v252
	v_add_u32_e32 v255, 0x20000, v253
	global_store_dwordx4 v254, v[62:65], s[74:75]
	global_store_dwordx4 v254, v[58:61], s[74:75] offset:16
	v_cvt_pk_bf16_f32 v246, v62, v63
	v_cvt_pk_bf16_f32 v247, v64, v65
	v_cvt_pk_bf16_f32 v248, v58, v59
	v_cvt_pk_bf16_f32 v249, v60, v61
	global_store_dwordx4 v255, v[246:249], s[98:99]
	s_nop 1
	global_store_dwordx4 v254, v[54:57], s[74:75] offset:512
	global_store_dwordx4 v254, v[50:53], s[74:75] offset:528
	v_cvt_pk_bf16_f32 v246, v54, v55
	v_cvt_pk_bf16_f32 v247, v56, v57
	v_cvt_pk_bf16_f32 v248, v50, v51
	v_cvt_pk_bf16_f32 v249, v52, v53
	global_store_dwordx4 v255, v[246:249], s[98:99] offset:256
	s_nop 1
	v_add_u32_e32 v254, 0x48000, v252
	v_add_u32_e32 v255, 0x24000, v253
; #define EM_PK8(a, b) ((u32x4){cvt_pk_bf16((a)[0], (a)[1]), cvt_pk_bf16((a)[2], (a)[3]), cvt_pk_bf16((b)[0], (b)[1]), cvt_pk_bf16((b)[2], (b)[3])})
;     __device__ __forceinline__ void operator()(const f32x4 (&acc)[2][2][4][2], const Unit& u, int wr, int wc, int fr, int fq) const {
;     ...
;                     else if (pn < 4) { const int c = col - 512; float* ko = (samp ? out + o_ks + (size_t)(row - mp) * 512 : out + o_kp + (size_t)row * 512) + c; *(f32x4*)ko = v0; *(f32x4*)(ko + 4) = v1;
;                         if (!samp) *(u32x4*)(Kb + (size_t)row * 512 + c) = EM_PK8(v0, v1); }
;                     else if (pn < 6) { const int c = col - 1024; float* vo = (samp ? out + o_vs + (size_t)(row - mp) * 512 : out + o_vp + (size_t)row * 512) + c; *(f32x4*)vo = v0; *(f32x4*)(vo + 4) = v1;
;                         if (!samp) *(u32x4*)(Vb + (size_t)row * 512 + c) = EM_PK8(v0, v1); }
	global_store_dwordx4 v254, v[46:49], s[74:75]
	global_store_dwordx4 v254, v[42:45], s[74:75] offset:16
	v_cvt_pk_bf16_f32 v246, v46, v47
	v_cvt_pk_bf16_f32 v247, v48, v49
	v_cvt_pk_bf16_f32 v248, v42, v43
	v_cvt_pk_bf16_f32 v249, v44, v45
	global_store_dwordx4 v255, v[246:249], s[98:99]
	s_nop 1
	global_store_dwordx4 v254, v[38:41], s[74:75] offset:512
	global_store_dwordx4 v254, v[34:37], s[74:75] offset:528
	v_cvt_pk_bf16_f32 v246, v38, v39
	v_cvt_pk_bf16_f32 v247, v40, v41
	v_cvt_pk_bf16_f32 v248, v34, v35
	v_cvt_pk_bf16_f32 v249, v36, v37
	global_store_dwordx4 v255, v[246:249], s[98:99] offset:256
	s_nop 1
	v_add_u32_e32 v254, 0x50000, v252
	v_add_u32_e32 v255, 0x28000, v253
	global_store_dwordx4 v254, v[30:33], s[74:75]
	global_store_dwordx4 v254, v[26:29], s[74:75] offset:16
	v_cvt_pk_bf16_f32 v246, v30, v31
	v_cvt_pk_bf16_f32 v247, v32, v33
	v_cvt_pk_bf16_f32 v248, v26, v27
	v_cvt_pk_bf16_f32 v249, v28, v29
	global_store_dwordx4 v255, v[246:249], s[98:99]
	s_nop 1
	global_store_dwordx4 v254, v[22:25], s[74:75] offset:512
	global_store_dwordx4 v254, v[18:21], s[74:75] offset:528
	v_cvt_pk_bf16_f32 v246, v22, v23
	v_cvt_pk_bf16_f32 v247, v24, v25
	v_cvt_pk_bf16_f32 v248, v18, v19
	v_cvt_pk_bf16_f32 v249, v20, v21
	global_store_dwordx4 v255, v[246:249], s[98:99] offset:256
	s_nop 1
	v_add_u32_e32 v254, 0x58000, v252
	v_add_u32_e32 v255, 0x2c000, v253
	global_store_dwordx4 v254, v[14:17], s[74:75]
	global_store_dwordx4 v254, v[10:13], s[74:75] offset:16
	v_cvt_pk_bf16_f32 v246, v14, v15
	v_cvt_pk_bf16_f32 v247, v16, v17
	v_cvt_pk_bf16_f32 v248, v10, v11
	v_cvt_pk_bf16_f32 v249, v12, v13
	global_store_dwordx4 v255, v[246:249], s[98:99]
	s_nop 1
	global_store_dwordx4 v254, v[6:9], s[74:75] offset:512
	global_store_dwordx4 v254, v[2:5], s[74:75] offset:528
	v_cvt_pk_bf16_f32 v246, v6, v7
	v_cvt_pk_bf16_f32 v247, v8, v9
	v_cvt_pk_bf16_f32 v248, v2, v3
	v_cvt_pk_bf16_f32 v249, v4, v5
	global_store_dwordx4 v255, v[246:249], s[98:99] offset:256
	s_nop 1
	s_branch .LBB0_945
.Lp4epi_V:
	v_readlane_b32 s98, v244, 26
	v_readlane_b32 s99, v244, 27
	v_lshl_add_u32 v254, s6, 8, v1
	v_lshl_or_b32 v255, s8, 8, v163
	v_lshlrev_b32_e32 v252, 11, v254
	v_lshl_add_u32 v252, v255, 2, v252
	v_add_u32_e32 v252, 0xfffff000, v252
	v_lshlrev_b32_e32 v253, 10, v254
	v_lshl_add_u32 v253, v255, 1, v253
	v_add_u32_e32 v253, 0xfffff800, v253
	v_mov_b32_e32 v254, v252
	v_mov_b32_e32 v255, v253
	global_store_dwordx4 v254, v[126:129], s[72:73]
	global_store_dwordx4 v254, v[122:125], s[72:73] offset:16
	v_cvt_pk_bf16_f32 v246, v126, v127
	v_cvt_pk_bf16_f32 v247, v128, v129
	v_cvt_pk_bf16_f32 v248, v122, v123
	v_cvt_pk_bf16_f32 v249, v124, v125
	global_store_dwordx4 v255, v[246:249], s[98:99]
	s_nop 1
	global_store_dwordx4 v254, v[118:121], s[72:73] offset:512
	global_store_dwordx4 v254, v[114:117], s[72:73] offset:528
	v_cvt_pk_bf16_f32 v246, v118, v119
	v_cvt_pk_bf16_f32 v247, v120, v121
	v_cvt_pk_bf16_f32 v248, v114, v115
	v_cvt_pk_bf16_f32 v249, v116, v117
	global_store_dwordx4 v255, v[246:249], s[98:99] offset:256
	s_nop 1
	v_add_u32_e32 v254, 0x8000, v252
	v_add_u32_e32 v255, 0x4000, v253
	global_store_dwordx4 v254, v[110:113], s[72:73]
	global_store_dwordx4 v254, v[106:109], s[72:73] offset:16
	v_cvt_pk_bf16_f32 v246, v110, v111
	v_cvt_pk_bf16_f32 v247, v112, v113
	v_cvt_pk_bf16_f32 v248, v106, v107
	v_cvt_pk_bf16_f32 v249, v108, v109
	global_store_dwordx4 v255, v[246:249], s[98:99]
	s_nop 1
	global_store_dwordx4 v254, v[102:105], s[72:73] offset:512
	global_store_dwordx4 v254, v[98:101], s[72:73] offset:528
	v_cvt_pk_bf16_f32 v246, v102, v103
	v_cvt_pk_bf16_f32 v247, v104, v105
	v_cvt_pk_bf16_f32 v248, v98, v99
	v_cvt_pk_bf16_f32 v249, v100, v101
	global_store_dwordx4 v255, v[246:249], s[98:99] offset:256
	s_nop 1
	v_add_u32_e32 v254, 0x10000, v252
	v_add_u32_e32 v255, 0x8000, v253
	global_store_dwordx4 v254, v[94:97], s[72:73]
	global_store_dwordx4 v254, v[90:93], s[72:73] offset:16
	v_cvt_pk_bf16_f32 v246, v94, v95
	v_cvt_pk_bf16_f32 v247, v96, v97
	v_cvt_pk_bf16_f32 v248, v90, v91
	v_cvt_pk_bf16_f32 v249, v92, v93
	global_store_dwordx4 v255, v[246:249], s[98:99]
	s_nop 1
	global_store_dwordx4 v254, v[86:89], s[72:73] offset:512
	global_store_dwordx4 v254, v[82:85], s[72:73] offset:528
	v_cvt_pk_bf16_f32 v246, v86, v87
	v_cvt_pk_bf16_f32 v247, v88, v89
	v_cvt_pk_bf16_f32 v248, v82, v83
	v_cvt_pk_bf16_f32 v249, v84, v85
	global_store_dwordx4 v255, v[246:249], s[98:99] offset:256
	s_nop 1
	v_add_u32_e32 v254, 0x18000, v252
	v_add_u32_e32 v255, 0xc000, v253
	global_store_dwordx4 v254, v[78:81], s[72:73]
	global_store_dwordx4 v254, v[74:77], s[72:73] offset:16
	v_cvt_pk_bf16_f32 v246, v78, v79
	v_cvt_pk_bf16_f32 v247, v80, v81
	v_cvt_pk_bf16_f32 v248, v74, v75
	v_cvt_pk_bf16_f32 v249, v76, v77
	global_store_dwordx4 v255, v[246:249], s[98:99]
	s_nop 1
	global_store_dwordx4 v254, v[70:73], s[72:73] offset:512
	global_store_dwordx4 v254, v[66:69], s[72:73] offset:528
	v_cvt_pk_bf16_f32 v246, v70, v71
	v_cvt_pk_bf16_f32 v247, v72, v73
	v_cvt_pk_bf16_f32 v248, v66, v67
; #define EM_PK8(a, b) ((u32x4){cvt_pk_bf16((a)[0], (a)[1]), cvt_pk_bf16((a)[2], (a)[3]), cvt_pk_bf16((b)[0], (b)[1]), cvt_pk_bf16((b)[2], (b)[3])})
;     __device__ __forceinline__ void operator()(const f32x4 (&acc)[2][2][4][2], const Unit& u, int wr, int wc, int fr, int fq) const {
;     ...
;                     if (samp || pn == 14) { float* pp = P + (size_t)row * 3840 + col; *(f32x4*)pp = v0; *(f32x4*)(pp + 4) = v1; }
;     ...
;                     else if (pn < 6) { const int c = col - 1024; float* vo = (samp ? out + o_vs + (size_t)(row - mp) * 512 : out + o_vp + (size_t)row * 512) + c; *(f32x4*)vo = v0; *(f32x4*)(vo + 4) = v1;
;                         if (!samp) *(u32x4*)(Vb + (size_t)row * 512 + c) = EM_PK8(v0, v1); }
	v_cvt_pk_bf16_f32 v249, v68, v69
	global_store_dwordx4 v255, v[246:249], s[98:99] offset:256
	s_nop 1
	v_add_u32_e32 v254, 0x40000, v252
	v_add_u32_e32 v255, 0x20000, v253
	global_store_dwordx4 v254, v[62:65], s[72:73]
	global_store_dwordx4 v254, v[58:61], s[72:73] offset:16
	v_cvt_pk_bf16_f32 v246, v62, v63
	v_cvt_pk_bf16_f32 v247, v64, v65
	v_cvt_pk_bf16_f32 v248, v58, v59
	v_cvt_pk_bf16_f32 v249, v60, v61
	global_store_dwordx4 v255, v[246:249], s[98:99]
	s_nop 1
	global_store_dwordx4 v254, v[54:57], s[72:73] offset:512
	global_store_dwordx4 v254, v[50:53], s[72:73] offset:528
	v_cvt_pk_bf16_f32 v246, v54, v55
	v_cvt_pk_bf16_f32 v247, v56, v57
	v_cvt_pk_bf16_f32 v248, v50, v51
	v_cvt_pk_bf16_f32 v249, v52, v53
	global_store_dwordx4 v255, v[246:249], s[98:99] offset:256
	s_nop 1
	v_add_u32_e32 v254, 0x48000, v252
	v_add_u32_e32 v255, 0x24000, v253
	global_store_dwordx4 v254, v[46:49], s[72:73]
	global_store_dwordx4 v254, v[42:45], s[72:73] offset:16
	v_cvt_pk_bf16_f32 v246, v46, v47
	v_cvt_pk_bf16_f32 v247, v48, v49
	v_cvt_pk_bf16_f32 v248, v42, v43
	v_cvt_pk_bf16_f32 v249, v44, v45
	global_store_dwordx4 v255, v[246:249], s[98:99]
	s_nop 1
	global_store_dwordx4 v254, v[38:41], s[72:73] offset:512
	global_store_dwordx4 v254, v[34:37], s[72:73] offset:528
	v_cvt_pk_bf16_f32 v246, v38, v39
	v_cvt_pk_bf16_f32 v247, v40, v41
	v_cvt_pk_bf16_f32 v248, v34, v35
	v_cvt_pk_bf16_f32 v249, v36, v37
	global_store_dwordx4 v255, v[246:249], s[98:99] offset:256
	s_nop 1
	v_add_u32_e32 v254, 0x50000, v252
	v_add_u32_e32 v255, 0x28000, v253
	global_store_dwordx4 v254, v[30:33], s[72:73]
	global_store_dwordx4 v254, v[26:29], s[72:73] offset:16
	v_cvt_pk_bf16_f32 v246, v30, v31
	v_cvt_pk_bf16_f32 v247, v32, v33
	v_cvt_pk_bf16_f32 v248, v26, v27
	v_cvt_pk_bf16_f32 v249, v28, v29
	global_store_dwordx4 v255, v[246:249], s[98:99]
	s_nop 1
	global_store_dwordx4 v254, v[22:25], s[72:73] offset:512
	global_store_dwordx4 v254, v[18:21], s[72:73] offset:528
	v_cvt_pk_bf16_f32 v246, v22, v23
	v_cvt_pk_bf16_f32 v247, v24, v25
	v_cvt_pk_bf16_f32 v248, v18, v19
	v_cvt_pk_bf16_f32 v249, v20, v21
	global_store_dwordx4 v255, v[246:249], s[98:99] offset:256
	s_nop 1
	v_add_u32_e32 v254, 0x58000, v252
	v_add_u32_e32 v255, 0x2c000, v253
	global_store_dwordx4 v254, v[14:17], s[72:73]
	global_store_dwordx4 v254, v[10:13], s[72:73] offset:16
	v_cvt_pk_bf16_f32 v246, v14, v15
	v_cvt_pk_bf16_f32 v247, v16, v17
	v_cvt_pk_bf16_f32 v248, v10, v11
	v_cvt_pk_bf16_f32 v249, v12, v13
	global_store_dwordx4 v255, v[246:249], s[98:99]
	s_nop 1
	global_store_dwordx4 v254, v[6:9], s[72:73] offset:512
	global_store_dwordx4 v254, v[2:5], s[72:73] offset:528
	v_cvt_pk_bf16_f32 v246, v6, v7
	v_cvt_pk_bf16_f32 v247, v8, v9
	v_cvt_pk_bf16_f32 v248, v2, v3
	v_cvt_pk_bf16_f32 v249, v4, v5
	global_store_dwordx4 v255, v[246:249], s[98:99] offset:256
	s_nop 1
	s_branch .LBB0_945
.Lp4epi_D:
	v_lshl_add_u32 v254, s6, 8, v1
	v_lshl_or_b32 v255, s8, 8, v163
	v_mul_u32_u24_e32 v254, 0x3c00, v254
	v_lshl_add_u32 v254, v255, 2, v254
	global_store_dwordx4 v254, v[126:129], s[88:89]
	global_store_dwordx4 v254, v[122:125], s[88:89] offset:16
	global_store_dwordx4 v254, v[118:121], s[88:89] offset:512
	global_store_dwordx4 v254, v[114:117], s[88:89] offset:528
	v_add_u32_e32 v255, 0x3c000, v254
	global_store_dwordx4 v255, v[110:113], s[88:89]
	global_store_dwordx4 v255, v[106:109], s[88:89] offset:16
	global_store_dwordx4 v255, v[102:105], s[88:89] offset:512
	global_store_dwordx4 v255, v[98:101], s[88:89] offset:528
	v_add_u32_e32 v255, 0x78000, v254
	global_store_dwordx4 v255, v[94:97], s[88:89]
	global_store_dwordx4 v255, v[90:93], s[88:89] offset:16
	global_store_dwordx4 v255, v[86:89], s[88:89] offset:512
	global_store_dwordx4 v255, v[82:85], s[88:89] offset:528
	v_add_u32_e32 v255, 0xb4000, v254
	global_store_dwordx4 v255, v[78:81], s[88:89]
	global_store_dwordx4 v255, v[74:77], s[88:89] offset:16
	global_store_dwordx4 v255, v[70:73], s[88:89] offset:512
	global_store_dwordx4 v255, v[66:69], s[88:89] offset:528
	v_add_u32_e32 v255, 0x1e0000, v254
	global_store_dwordx4 v255, v[62:65], s[88:89]
	global_store_dwordx4 v255, v[58:61], s[88:89] offset:16
	global_store_dwordx4 v255, v[54:57], s[88:89] offset:512
	global_store_dwordx4 v255, v[50:53], s[88:89] offset:528
	v_add_u32_e32 v255, 0x21c000, v254
	global_store_dwordx4 v255, v[46:49], s[88:89]
	global_store_dwordx4 v255, v[42:45], s[88:89] offset:16
	global_store_dwordx4 v255, v[38:41], s[88:89] offset:512
	global_store_dwordx4 v255, v[34:37], s[88:89] offset:528
	v_add_u32_e32 v255, 0x258000, v254
	global_store_dwordx4 v255, v[30:33], s[88:89]
	global_store_dwordx4 v255, v[26:29], s[88:89] offset:16
	global_store_dwordx4 v255, v[22:25], s[88:89] offset:512
	global_store_dwordx4 v255, v[18:21], s[88:89] offset:528
	v_add_u32_e32 v255, 0x294000, v254
	global_store_dwordx4 v255, v[14:17], s[88:89]
	global_store_dwordx4 v255, v[10:13], s[88:89] offset:16
	global_store_dwordx4 v255, v[6:9], s[88:89] offset:512
	global_store_dwordx4 v255, v[2:5], s[88:89] offset:528
	s_branch .LBB0_945
